# split-K slab epilogue (w_out quarter units, w_down tail units): 32-step load/wait/store chain replaced by 16 gate loads in flight with counted waits
# speedup vs baseline: 1.0033x; 1.0033x over previous
.LBB0_1496:
	s_nop 15
	s_nop 7
	v_readlane_b32 s42, v254, 61
	v_mov_b32_e32 v4, v180
	v_mov_b32_e32 v2, v181
	s_andn2_b64 vcc, exec, s[16:17]
	s_mov_b32 s82, s42
	v_readlane_b32 s43, v254, 62
	s_cbranch_vccnz .LBB0_1501
	s_lshl_b32 s27, s46, 8
	s_or_b32 s27, s27, s69
	v_lshl_add_u32 v2, v2, 2, s27
	s_mov_b64 s[42:43], -1
	s_cmp_lt_i32 s4, 0
	v_ashrrev_i32_e32 v3, 31, v2
	s_cbranch_scc1 .LBB0_1499
	v_add_u32_e32 v6, s68, v4
	v_lshl_add_u32 v5, s38, 8, v6
	v_add_u32_e32 v7, 0xffffe000, v5
	v_ashrrev_i32_e32 v7, 5, v7
	v_add_u32_e32 v7, 2, v7
	v_mov_b64_e32 v[8:9], s[10:11]
	v_mad_i64_i32 v[12:13], s[42:43], v7, s72, v[8:9]
	v_lshlrev_b64 v[10:11], 2, v[2:3]
	v_lshl_add_u64 v[18:19], v[12:13], 0, v[10:11]
	global_load_dwordx4 v[188:191], v[18:19], off
	global_load_dwordx4 v[192:195], v[18:19], off offset:64
	global_load_dwordx4 v[196:199], v[18:19], off offset:512
	global_load_dwordx4 v[200:203], v[18:19], off offset:576
	v_add_u32_e32 v32, 0xffffe010, v5
	v_ashrrev_i32_e32 v32, 5, v32
	v_add_u32_e32 v32, 2, v32
	v_mad_i64_i32 v[186:187], s[42:43], v32, s72, v[8:9]
	v_lshl_add_u64 v[186:187], v[186:187], 0, v[10:11]
	global_load_dwordx4 v[204:207], v[186:187], off
	global_load_dwordx4 v[208:211], v[186:187], off offset:64
	global_load_dwordx4 v[212:215], v[186:187], off offset:512
	global_load_dwordx4 v[216:219], v[186:187], off offset:576
	v_add_u32_e32 v32, 0xffffe020, v5
	v_ashrrev_i32_e32 v32, 5, v32
	v_add_u32_e32 v32, 2, v32
	v_mad_i64_i32 v[186:187], s[42:43], v32, s72, v[8:9]
	v_lshl_add_u64 v[186:187], v[186:187], 0, v[10:11]
	global_load_dwordx4 v[220:223], v[186:187], off
	global_load_dwordx4 v[224:227], v[186:187], off offset:64
	global_load_dwordx4 v[228:231], v[186:187], off offset:512
	global_load_dwordx4 v[232:235], v[186:187], off offset:576
	v_add_u32_e32 v32, 0xffffe030, v5
	v_ashrrev_i32_e32 v32, 5, v32
	v_add_u32_e32 v32, 2, v32
	v_mad_i64_i32 v[186:187], s[42:43], v32, s72, v[8:9]
	v_lshl_add_u64 v[186:187], v[186:187], 0, v[10:11]
	global_load_dwordx4 v[236:239], v[186:187], off
	global_load_dwordx4 v[240:243], v[186:187], off offset:64
	global_load_dwordx4 v[244:247], v[186:187], off offset:512
	global_load_dwordx4 v[248:251], v[186:187], off offset:576
	v_add_u32_e32 v32, 0xffffe080, v5
	v_ashrrev_i32_e32 v32, 5, v32
	v_add_u32_e32 v32, 2, v32
	v_mad_i64_i32 v[24:25], s[42:43], v32, s72, v[8:9]
	v_lshl_add_u64 v[24:25], v[24:25], 0, v[10:11]
	v_add_u32_e32 v32, 0xffffe090, v5
	v_ashrrev_i32_e32 v32, 5, v32
	v_add_u32_e32 v32, 2, v32
	v_mad_i64_i32 v[26:27], s[42:43], v32, s72, v[8:9]
	v_lshl_add_u64 v[26:27], v[26:27], 0, v[10:11]
	v_add_u32_e32 v32, 0xffffe0a0, v5
	v_ashrrev_i32_e32 v32, 5, v32
	v_add_u32_e32 v32, 2, v32
	v_mad_i64_i32 v[28:29], s[42:43], v32, s72, v[8:9]
	v_lshl_add_u64 v[28:29], v[28:29], 0, v[10:11]
	s_ashr_i32 s39, s38, 31
	s_lshl_b64 s[42:43], s[4:5], 22
	s_lshl_b64 s[46:47], s[38:39], 21
	s_add_u32 s4, s66, s42
	s_addc_u32 s27, s67, s43
	v_ashrrev_i32_e32 v7, 31, v6
	s_add_u32 s46, s4, s46
	v_lshlrev_b64 v[20:21], 13, v[6:7]
	s_addc_u32 s47, s27, s47
	v_lshlrev_b64 v[12:13], 1, v[2:3]
	v_lshl_add_u64 v[20:21], s[46:47], 0, v[20:21]
	v_lshl_add_u64 v[20:21], v[20:21], 0, v[12:13]
	v_add_co_u32_e32 v22, vcc, s77, v20
	v_add_u32_e32 v7, 0xffffe010, v5
	s_nop 0
	v_addc_co_u32_e32 v23, vcc, -1, v21, vcc
	v_lshl_add_u64 v[20:21], v[20:21], 0, s[24:25]
	v_ashrrev_i32_e32 v7, 5, v7
	v_add_u32_e32 v7, 2, v7
	s_waitcnt vmcnt(15)
	v_pk_mul_f32 v[188:189], v[188:189], s[20:21] op_sel_hi:[1,0]
	v_pk_mul_f32 v[190:191], v[190:191], s[20:21] op_sel_hi:[1,0]
	v_pk_mul_f32 v[188:189], v[158:159], v[188:189]
	v_pk_mul_f32 v[190:191], v[160:161], v[190:191]
	v_cvt_pk_bf16_f32 v188, v188, v189
	s_nop 0
	v_cvt_pk_bf16_f32 v189, v190, v191
	global_store_dwordx2 v[22:23], v[188:189], off
	global_load_dwordx4 v[188:191], v[24:25], off
	s_waitcnt vmcnt(16)
	v_pk_mul_f32 v[192:193], v[192:193], s[20:21] op_sel_hi:[1,0]
	v_pk_mul_f32 v[194:195], v[194:195], s[20:21] op_sel_hi:[1,0]
	v_pk_mul_f32 v[192:193], v[154:155], v[192:193]
	v_pk_mul_f32 v[194:195], v[156:157], v[194:195]
	v_cvt_pk_bf16_f32 v192, v192, v193
	s_nop 0
	v_cvt_pk_bf16_f32 v193, v194, v195
	global_store_dwordx2 v[20:21], v[192:193], off offset:32
	global_load_dwordx4 v[192:195], v[24:25], off offset:64
	s_waitcnt vmcnt(17)
	v_pk_mul_f32 v[196:197], v[196:197], s[20:21] op_sel_hi:[1,0]
	v_pk_mul_f32 v[198:199], v[198:199], s[20:21] op_sel_hi:[1,0]
	v_pk_mul_f32 v[196:197], v[142:143], v[196:197]
	v_pk_mul_f32 v[198:199], v[144:145], v[198:199]
	v_cvt_pk_bf16_f32 v196, v196, v197
	s_nop 0
	v_cvt_pk_bf16_f32 v197, v198, v199
	global_store_dwordx2 v[20:21], v[196:197], off offset:256
	global_load_dwordx4 v[196:199], v[24:25], off offset:512
	v_mad_i64_i32 v[18:19], s[42:43], v7, s72, v[8:9]
	v_lshl_add_u64 v[18:19], v[18:19], 0, v[10:11]
	v_add_u32_e32 v7, 0xffffe020, v5
	v_ashrrev_i32_e32 v7, 5, v7
	v_add_u32_e32 v7, 2, v7
	s_waitcnt vmcnt(18)
	v_pk_mul_f32 v[200:201], v[200:201], s[20:21] op_sel_hi:[1,0]
	v_pk_mul_f32 v[202:203], v[202:203], s[20:21] op_sel_hi:[1,0]
	v_pk_mul_f32 v[200:201], v[138:139], v[200:201]
	v_pk_mul_f32 v[202:203], v[140:141], v[202:203]
	v_cvt_pk_bf16_f32 v200, v200, v201
	s_nop 0
	v_cvt_pk_bf16_f32 v201, v202, v203
	global_store_dwordx2 v[20:21], v[200:201], off offset:288
	global_load_dwordx4 v[200:203], v[24:25], off offset:576
	v_add_u32_e32 v20, 16, v6
	v_ashrrev_i32_e32 v21, 31, v20
	v_lshlrev_b64 v[20:21], 13, v[20:21]
	v_lshl_add_u64 v[20:21], s[46:47], 0, v[20:21]
	v_lshl_add_u64 v[20:21], v[20:21], 0, v[12:13]
	v_add_co_u32_e32 v22, vcc, s77, v20
	s_waitcnt vmcnt(19)
	v_pk_mul_f32 v[204:205], v[204:205], s[20:21] op_sel_hi:[1,0]
	v_addc_co_u32_e32 v23, vcc, -1, v21, vcc
	v_pk_mul_f32 v[206:207], v[206:207], s[20:21] op_sel_hi:[1,0]
	v_pk_mul_f32 v[204:205], v[150:151], v[204:205]
	v_pk_mul_f32 v[206:207], v[152:153], v[206:207]
	v_cvt_pk_bf16_f32 v204, v204, v205
	v_lshl_add_u64 v[20:21], v[20:21], 0, s[24:25]
	v_cvt_pk_bf16_f32 v205, v206, v207
	global_store_dwordx2 v[22:23], v[204:205], off
	global_load_dwordx4 v[204:207], v[26:27], off
	s_waitcnt vmcnt(20)
	v_pk_mul_f32 v[208:209], v[208:209], s[20:21] op_sel_hi:[1,0]
	v_pk_mul_f32 v[210:211], v[210:211], s[20:21] op_sel_hi:[1,0]
	v_pk_mul_f32 v[208:209], v[146:147], v[208:209]
	v_pk_mul_f32 v[210:211], v[148:149], v[210:211]
	v_cvt_pk_bf16_f32 v208, v208, v209
	s_nop 0
	v_cvt_pk_bf16_f32 v209, v210, v211
	global_store_dwordx2 v[20:21], v[208:209], off offset:32
	global_load_dwordx4 v[208:211], v[26:27], off offset:64
	s_waitcnt vmcnt(21)
	v_pk_mul_f32 v[212:213], v[212:213], s[20:21] op_sel_hi:[1,0]
	v_pk_mul_f32 v[214:215], v[214:215], s[20:21] op_sel_hi:[1,0]
	v_pk_mul_f32 v[212:213], v[134:135], v[212:213]
	v_pk_mul_f32 v[214:215], v[136:137], v[214:215]
	v_cvt_pk_bf16_f32 v212, v212, v213
	s_nop 0
	v_cvt_pk_bf16_f32 v213, v214, v215
	global_store_dwordx2 v[20:21], v[212:213], off offset:256
	global_load_dwordx4 v[212:215], v[26:27], off offset:512
	v_mad_i64_i32 v[18:19], s[42:43], v7, s72, v[8:9]
	v_lshl_add_u64 v[18:19], v[18:19], 0, v[10:11]
	v_add_u32_e32 v7, 0xffffe030, v5
	v_ashrrev_i32_e32 v7, 5, v7
	v_add_u32_e32 v7, 2, v7
	s_waitcnt vmcnt(22)
	v_pk_mul_f32 v[216:217], v[216:217], s[20:21] op_sel_hi:[1,0]
	v_pk_mul_f32 v[218:219], v[218:219], s[20:21] op_sel_hi:[1,0]
	v_pk_mul_f32 v[216:217], v[130:131], v[216:217]
	v_pk_mul_f32 v[218:219], v[132:133], v[218:219]
	v_cvt_pk_bf16_f32 v216, v216, v217
	s_nop 0
	v_cvt_pk_bf16_f32 v217, v218, v219
	global_store_dwordx2 v[20:21], v[216:217], off offset:288
	global_load_dwordx4 v[216:219], v[26:27], off offset:576
	v_add_u32_e32 v20, 32, v6
	v_ashrrev_i32_e32 v21, 31, v20
	v_lshlrev_b64 v[20:21], 13, v[20:21]
	v_lshl_add_u64 v[20:21], s[46:47], 0, v[20:21]
	v_lshl_add_u64 v[20:21], v[20:21], 0, v[12:13]
	v_add_co_u32_e32 v22, vcc, s77, v20
	s_waitcnt vmcnt(23)
	v_pk_mul_f32 v[220:221], v[220:221], s[20:21] op_sel_hi:[1,0]
	v_addc_co_u32_e32 v23, vcc, -1, v21, vcc
	v_pk_mul_f32 v[222:223], v[222:223], s[20:21] op_sel_hi:[1,0]
	v_pk_mul_f32 v[220:221], v[126:127], v[220:221]
	v_pk_mul_f32 v[222:223], v[128:129], v[222:223]
	v_cvt_pk_bf16_f32 v220, v220, v221
	v_lshl_add_u64 v[20:21], v[20:21], 0, s[24:25]
	v_cvt_pk_bf16_f32 v221, v222, v223
	global_store_dwordx2 v[22:23], v[220:221], off
	global_load_dwordx4 v[220:223], v[28:29], off
	s_waitcnt vmcnt(24)
	v_pk_mul_f32 v[224:225], v[224:225], s[20:21] op_sel_hi:[1,0]
	v_pk_mul_f32 v[226:227], v[226:227], s[20:21] op_sel_hi:[1,0]
	v_pk_mul_f32 v[224:225], v[122:123], v[224:225]
	v_pk_mul_f32 v[226:227], v[124:125], v[226:227]
	v_cvt_pk_bf16_f32 v224, v224, v225
	s_nop 0
	v_cvt_pk_bf16_f32 v225, v226, v227
	global_store_dwordx2 v[20:21], v[224:225], off offset:32
	global_load_dwordx4 v[224:227], v[28:29], off offset:64
	s_waitcnt vmcnt(25)
	v_pk_mul_f32 v[228:229], v[228:229], s[20:21] op_sel_hi:[1,0]
	v_pk_mul_f32 v[230:231], v[230:231], s[20:21] op_sel_hi:[1,0]
	v_pk_mul_f32 v[228:229], v[118:119], v[228:229]
	v_pk_mul_f32 v[230:231], v[120:121], v[230:231]
	v_cvt_pk_bf16_f32 v228, v228, v229
	s_nop 0
	v_cvt_pk_bf16_f32 v229, v230, v231
	global_store_dwordx2 v[20:21], v[228:229], off offset:256
	global_load_dwordx4 v[228:231], v[28:29], off offset:512
	v_mad_i64_i32 v[18:19], s[42:43], v7, s72, v[8:9]
	v_lshl_add_u64 v[18:19], v[18:19], 0, v[10:11]
	v_add_u32_e32 v7, 0xffffe080, v5
	v_ashrrev_i32_e32 v7, 5, v7
	v_add_u32_e32 v7, 2, v7
	s_waitcnt vmcnt(26)
	v_pk_mul_f32 v[232:233], v[232:233], s[20:21] op_sel_hi:[1,0]
	v_pk_mul_f32 v[234:235], v[234:235], s[20:21] op_sel_hi:[1,0]
	v_pk_mul_f32 v[232:233], v[110:111], v[232:233]
	v_pk_mul_f32 v[234:235], v[112:113], v[234:235]
	v_cvt_pk_bf16_f32 v232, v232, v233
	s_nop 0
	v_cvt_pk_bf16_f32 v233, v234, v235
	global_store_dwordx2 v[20:21], v[232:233], off offset:288
	global_load_dwordx4 v[232:235], v[28:29], off offset:576
	v_add_u32_e32 v20, 48, v6
	v_ashrrev_i32_e32 v21, 31, v20
	v_lshlrev_b64 v[20:21], 13, v[20:21]
	v_lshl_add_u64 v[20:21], s[46:47], 0, v[20:21]
	v_lshl_add_u64 v[20:21], v[20:21], 0, v[12:13]
	v_add_co_u32_e32 v22, vcc, s77, v20
	s_waitcnt vmcnt(27)
	v_pk_mul_f32 v[236:237], v[236:237], s[20:21] op_sel_hi:[1,0]
	v_addc_co_u32_e32 v23, vcc, -1, v21, vcc
	v_pk_mul_f32 v[238:239], v[238:239], s[20:21] op_sel_hi:[1,0]
	v_pk_mul_f32 v[236:237], v[114:115], v[236:237]
	v_pk_mul_f32 v[238:239], v[116:117], v[238:239]
	v_cvt_pk_bf16_f32 v236, v236, v237
	v_lshl_add_u64 v[20:21], v[20:21], 0, s[24:25]
	v_cvt_pk_bf16_f32 v237, v238, v239
	global_store_dwordx2 v[22:23], v[236:237], off
	s_waitcnt vmcnt(27)
	v_pk_mul_f32 v[240:241], v[240:241], s[20:21] op_sel_hi:[1,0]
	v_pk_mul_f32 v[242:243], v[242:243], s[20:21] op_sel_hi:[1,0]
	v_pk_mul_f32 v[240:241], v[106:107], v[240:241]
	v_pk_mul_f32 v[242:243], v[108:109], v[242:243]
	v_cvt_pk_bf16_f32 v240, v240, v241
	s_nop 0
	v_cvt_pk_bf16_f32 v241, v242, v243
	global_store_dwordx2 v[20:21], v[240:241], off offset:32
	s_waitcnt vmcnt(27)
	v_pk_mul_f32 v[244:245], v[244:245], s[20:21] op_sel_hi:[1,0]
	v_pk_mul_f32 v[246:247], v[246:247], s[20:21] op_sel_hi:[1,0]
	v_pk_mul_f32 v[244:245], v[102:103], v[244:245]
	v_pk_mul_f32 v[246:247], v[104:105], v[246:247]
	v_cvt_pk_bf16_f32 v244, v244, v245
	s_nop 0
	v_cvt_pk_bf16_f32 v245, v246, v247
	global_store_dwordx2 v[20:21], v[244:245], off offset:256
	v_mad_i64_i32 v[18:19], s[42:43], v7, s72, v[8:9]
	v_lshl_add_u64 v[18:19], v[18:19], 0, v[10:11]
	v_add_u32_e32 v7, 0xffffe090, v5
	v_ashrrev_i32_e32 v7, 5, v7
	v_add_u32_e32 v7, 2, v7
	s_waitcnt vmcnt(27)
	v_pk_mul_f32 v[248:249], v[248:249], s[20:21] op_sel_hi:[1,0]
	v_pk_mul_f32 v[250:251], v[250:251], s[20:21] op_sel_hi:[1,0]
	v_pk_mul_f32 v[248:249], v[98:99], v[248:249]
	v_pk_mul_f32 v[250:251], v[100:101], v[250:251]
	v_cvt_pk_bf16_f32 v248, v248, v249
	s_nop 0
	v_cvt_pk_bf16_f32 v249, v250, v251
	global_store_dwordx2 v[20:21], v[248:249], off offset:288
	v_add_u32_e32 v20, 0x80, v6
	v_ashrrev_i32_e32 v21, 31, v20
	v_lshlrev_b64 v[20:21], 13, v[20:21]
	v_lshl_add_u64 v[20:21], s[46:47], 0, v[20:21]
	v_lshl_add_u64 v[20:21], v[20:21], 0, v[12:13]
	v_add_co_u32_e32 v22, vcc, s77, v20
	s_waitcnt vmcnt(26)
	v_pk_mul_f32 v[188:189], v[188:189], s[20:21] op_sel_hi:[1,0]
	v_addc_co_u32_e32 v23, vcc, -1, v21, vcc
	v_pk_mul_f32 v[190:191], v[190:191], s[20:21] op_sel_hi:[1,0]
	v_pk_mul_f32 v[188:189], v[94:95], v[188:189]
	v_pk_mul_f32 v[190:191], v[96:97], v[190:191]
	v_cvt_pk_bf16_f32 v188, v188, v189
	v_lshl_add_u64 v[20:21], v[20:21], 0, s[24:25]
	v_cvt_pk_bf16_f32 v189, v190, v191
	global_store_dwordx2 v[22:23], v[188:189], off
	s_waitcnt vmcnt(25)
	v_pk_mul_f32 v[192:193], v[192:193], s[20:21] op_sel_hi:[1,0]
	v_pk_mul_f32 v[194:195], v[194:195], s[20:21] op_sel_hi:[1,0]
	v_pk_mul_f32 v[192:193], v[90:91], v[192:193]
	v_pk_mul_f32 v[194:195], v[92:93], v[194:195]
	v_cvt_pk_bf16_f32 v192, v192, v193
	s_nop 0
	v_cvt_pk_bf16_f32 v193, v194, v195
	global_store_dwordx2 v[20:21], v[192:193], off offset:32
	s_waitcnt vmcnt(24)
	v_pk_mul_f32 v[196:197], v[196:197], s[20:21] op_sel_hi:[1,0]
	v_pk_mul_f32 v[198:199], v[198:199], s[20:21] op_sel_hi:[1,0]
	v_pk_mul_f32 v[196:197], v[86:87], v[196:197]
	v_pk_mul_f32 v[198:199], v[88:89], v[198:199]
	v_cvt_pk_bf16_f32 v196, v196, v197
	s_nop 0
	v_cvt_pk_bf16_f32 v197, v198, v199
	global_store_dwordx2 v[20:21], v[196:197], off offset:256
	v_mad_i64_i32 v[18:19], s[42:43], v7, s72, v[8:9]
	v_lshl_add_u64 v[18:19], v[18:19], 0, v[10:11]
	v_add_u32_e32 v7, 0xffffe0a0, v5
	v_ashrrev_i32_e32 v7, 5, v7
	v_add_u32_e32 v7, 2, v7
	v_add_u32_e32 v5, 0xffffe0b0, v5
	v_ashrrev_i32_e32 v5, 5, v5
	v_add_u32_e32 v5, 2, v5
	s_waitcnt vmcnt(23)
	v_pk_mul_f32 v[200:201], v[200:201], s[20:21] op_sel_hi:[1,0]
	v_pk_mul_f32 v[202:203], v[202:203], s[20:21] op_sel_hi:[1,0]
	v_pk_mul_f32 v[200:201], v[78:79], v[200:201]
	v_pk_mul_f32 v[202:203], v[80:81], v[202:203]
	v_cvt_pk_bf16_f32 v200, v200, v201
	s_nop 0
	v_cvt_pk_bf16_f32 v201, v202, v203
	global_store_dwordx2 v[20:21], v[200:201], off offset:288
	v_add_u32_e32 v20, 0x90, v6
	v_ashrrev_i32_e32 v21, 31, v20
	v_lshlrev_b64 v[20:21], 13, v[20:21]
	v_lshl_add_u64 v[20:21], s[46:47], 0, v[20:21]
	v_lshl_add_u64 v[20:21], v[20:21], 0, v[12:13]
	v_add_co_u32_e32 v22, vcc, s77, v20
	s_waitcnt vmcnt(22)
	v_pk_mul_f32 v[204:205], v[204:205], s[20:21] op_sel_hi:[1,0]
	v_addc_co_u32_e32 v23, vcc, -1, v21, vcc
	v_pk_mul_f32 v[206:207], v[206:207], s[20:21] op_sel_hi:[1,0]
	v_pk_mul_f32 v[204:205], v[82:83], v[204:205]
	v_pk_mul_f32 v[206:207], v[84:85], v[206:207]
	v_cvt_pk_bf16_f32 v204, v204, v205
	v_lshl_add_u64 v[20:21], v[20:21], 0, s[24:25]
	v_cvt_pk_bf16_f32 v205, v206, v207
	global_store_dwordx2 v[22:23], v[204:205], off
	s_waitcnt vmcnt(21)
	v_pk_mul_f32 v[208:209], v[208:209], s[20:21] op_sel_hi:[1,0]
	v_pk_mul_f32 v[210:211], v[210:211], s[20:21] op_sel_hi:[1,0]
	v_pk_mul_f32 v[208:209], v[74:75], v[208:209]
	v_pk_mul_f32 v[210:211], v[76:77], v[210:211]
	v_cvt_pk_bf16_f32 v208, v208, v209
	s_nop 0
	v_cvt_pk_bf16_f32 v209, v210, v211
	global_store_dwordx2 v[20:21], v[208:209], off offset:32
	s_waitcnt vmcnt(20)
	v_pk_mul_f32 v[212:213], v[212:213], s[20:21] op_sel_hi:[1,0]
	v_pk_mul_f32 v[214:215], v[214:215], s[20:21] op_sel_hi:[1,0]
	v_pk_mul_f32 v[212:213], v[70:71], v[212:213]
	v_pk_mul_f32 v[214:215], v[72:73], v[214:215]
	v_cvt_pk_bf16_f32 v212, v212, v213
	s_nop 0
	v_cvt_pk_bf16_f32 v213, v214, v215
	global_store_dwordx2 v[20:21], v[212:213], off offset:256
	v_mad_i64_i32 v[18:19], s[42:43], v7, s72, v[8:9]
	v_lshl_add_u64 v[18:19], v[18:19], 0, v[10:11]
	v_mad_i64_i32 v[8:9], s[42:43], v5, s72, v[8:9]
	s_mov_b64 s[42:43], 0
	s_waitcnt vmcnt(19)
	v_pk_mul_f32 v[216:217], v[216:217], s[20:21] op_sel_hi:[1,0]
	v_pk_mul_f32 v[218:219], v[218:219], s[20:21] op_sel_hi:[1,0]
	v_pk_mul_f32 v[216:217], v[62:63], v[216:217]
	v_pk_mul_f32 v[218:219], v[64:65], v[218:219]
	v_cvt_pk_bf16_f32 v216, v216, v217
	s_nop 0
	v_cvt_pk_bf16_f32 v217, v218, v219
	global_store_dwordx2 v[20:21], v[216:217], off offset:288
	v_add_u32_e32 v20, 0xa0, v6
	v_ashrrev_i32_e32 v21, 31, v20
	v_lshlrev_b64 v[20:21], 13, v[20:21]
	v_lshl_add_u64 v[20:21], s[46:47], 0, v[20:21]
	v_lshl_add_u64 v[20:21], v[20:21], 0, v[12:13]
	v_add_co_u32_e32 v22, vcc, s77, v20
	v_add_u32_e32 v6, 0xb0, v6
	s_nop 0
	v_addc_co_u32_e32 v23, vcc, -1, v21, vcc
	v_lshl_add_u64 v[20:21], v[20:21], 0, s[24:25]
	v_ashrrev_i32_e32 v7, 31, v6
	v_lshlrev_b64 v[6:7], 13, v[6:7]
	v_lshl_add_u64 v[6:7], s[46:47], 0, v[6:7]
	v_lshl_add_u64 v[12:13], v[6:7], 0, v[12:13]
	v_add_co_u32_e32 v6, vcc, s77, v12
	s_waitcnt vmcnt(18)
	v_pk_mul_f32 v[220:221], v[220:221], s[20:21] op_sel_hi:[1,0]
	v_pk_mul_f32 v[222:223], v[222:223], s[20:21] op_sel_hi:[1,0]
	v_pk_mul_f32 v[220:221], v[66:67], v[220:221]
	v_pk_mul_f32 v[222:223], v[68:69], v[222:223]
	v_cvt_pk_bf16_f32 v220, v220, v221
	v_addc_co_u32_e32 v7, vcc, -1, v13, vcc
	v_cvt_pk_bf16_f32 v221, v222, v223
	global_store_dwordx2 v[22:23], v[220:221], off
	s_waitcnt vmcnt(17)
	v_pk_mul_f32 v[224:225], v[224:225], s[20:21] op_sel_hi:[1,0]
	v_pk_mul_f32 v[226:227], v[226:227], s[20:21] op_sel_hi:[1,0]
	v_pk_mul_f32 v[224:225], v[58:59], v[224:225]
	v_pk_mul_f32 v[226:227], v[60:61], v[226:227]
	v_cvt_pk_bf16_f32 v224, v224, v225
	s_nop 0
	v_cvt_pk_bf16_f32 v225, v226, v227
	global_store_dwordx2 v[20:21], v[224:225], off offset:32
	s_waitcnt vmcnt(16)
	v_pk_mul_f32 v[228:229], v[228:229], s[20:21] op_sel_hi:[1,0]
	v_pk_mul_f32 v[230:231], v[230:231], s[20:21] op_sel_hi:[1,0]
	v_pk_mul_f32 v[228:229], v[54:55], v[228:229]
	v_pk_mul_f32 v[230:231], v[56:57], v[230:231]
	v_cvt_pk_bf16_f32 v228, v228, v229
	s_nop 0
	v_cvt_pk_bf16_f32 v229, v230, v231
	global_store_dwordx2 v[20:21], v[228:229], off offset:256
	v_lshl_add_u64 v[18:19], v[8:9], 0, v[10:11]
	s_waitcnt vmcnt(15)
	v_pk_mul_f32 v[10:11], v[232:233], s[20:21] op_sel_hi:[1,0]
	v_pk_mul_f32 v[8:9], v[234:235], s[20:21] op_sel_hi:[1,0]
	v_pk_mul_f32 v[10:11], v[46:47], v[10:11]
	v_pk_mul_f32 v[8:9], v[48:49], v[8:9]
	v_cvt_pk_bf16_f32 v10, v10, v11
	s_nop 0
	v_cvt_pk_bf16_f32 v11, v8, v9
	global_store_dwordx2 v[20:21], v[10:11], off offset:288
	global_load_dwordx4 v[8:11], v[18:19], off
	s_waitcnt vmcnt(0)
	v_pk_mul_f32 v[8:9], v[8:9], s[20:21] op_sel_hi:[1,0]
	v_pk_mul_f32 v[10:11], v[10:11], s[20:21] op_sel_hi:[1,0]
	v_pk_mul_f32 v[8:9], v[50:51], v[8:9]
	v_pk_mul_f32 v[10:11], v[52:53], v[10:11]
	v_cvt_pk_bf16_f32 v8, v8, v9
	s_nop 0
	v_cvt_pk_bf16_f32 v9, v10, v11
	global_store_dwordx2 v[6:7], v[8:9], off
	global_load_dwordx4 v[6:9], v[18:19], off offset:64
	v_lshl_add_u64 v[10:11], v[12:13], 0, s[24:25]
	s_waitcnt vmcnt(0)
	v_pk_mul_f32 v[6:7], v[6:7], s[20:21] op_sel_hi:[1,0]
	v_pk_mul_f32 v[8:9], v[8:9], s[20:21] op_sel_hi:[1,0]
	v_pk_mul_f32 v[6:7], v[42:43], v[6:7]
	v_pk_mul_f32 v[8:9], v[44:45], v[8:9]
	v_cvt_pk_bf16_f32 v6, v6, v7
	s_nop 0
	v_cvt_pk_bf16_f32 v7, v8, v9
	global_store_dwordx2 v[10:11], v[6:7], off offset:32
	global_load_dwordx4 v[6:9], v[18:19], off offset:512
	s_waitcnt vmcnt(0)
	v_pk_mul_f32 v[6:7], v[6:7], s[20:21] op_sel_hi:[1,0]
	v_pk_mul_f32 v[8:9], v[8:9], s[20:21] op_sel_hi:[1,0]
	v_pk_mul_f32 v[6:7], v[38:39], v[6:7]
	v_pk_mul_f32 v[8:9], v[40:41], v[8:9]
	v_cvt_pk_bf16_f32 v6, v6, v7
	s_nop 0
	v_cvt_pk_bf16_f32 v7, v8, v9
	global_store_dwordx2 v[10:11], v[6:7], off offset:256
	global_load_dwordx4 v[6:9], v[18:19], off offset:576
	s_waitcnt vmcnt(0)
	v_pk_mul_f32 v[6:7], v[6:7], s[20:21] op_sel_hi:[1,0]
	v_pk_mul_f32 v[8:9], v[8:9], s[20:21] op_sel_hi:[1,0]
	v_pk_mul_f32 v[6:7], v[34:35], v[6:7]
	v_pk_mul_f32 v[8:9], v[36:37], v[8:9]
	v_cvt_pk_bf16_f32 v6, v6, v7
	s_nop 0
	v_cvt_pk_bf16_f32 v7, v8, v9
	global_store_dwordx2 v[10:11], v[6:7], off offset:288

.LBB0_1693:
	s_nop 15
	s_nop 7
	s_lshl_b32 s29, s33, 8
	v_mov_b32_e32 v2, v178
	v_mov_b32_e32 v3, v179
	s_or_b32 s29, s29, s56
	s_mov_b64 s[40:41], -1
	v_lshl_add_u32 v4, v3, 2, s29
	s_cmp_lt_i32 s8, 0
	v_ashrrev_i32_e32 v5, 31, v4
	s_cbranch_scc1 .LBB0_1696
	v_add_u32_e32 v6, s55, v2
	v_lshl_add_u32 v3, s38, 8, v6
	v_add_u32_e32 v7, 0xffffe000, v3
	v_ashrrev_i32_e32 v7, 5, v7
	v_add_u32_e32 v7, 2, v7
	v_mov_b64_e32 v[8:9], s[12:13]
	v_mad_i64_i32 v[12:13], s[40:41], v7, s59, v[8:9]
	v_lshlrev_b64 v[10:11], 2, v[4:5]
	v_lshl_add_u64 v[18:19], v[12:13], 0, v[10:11]
	global_load_dwordx4 v[188:191], v[18:19], off
	global_load_dwordx4 v[192:195], v[18:19], off offset:64
	global_load_dwordx4 v[196:199], v[18:19], off offset:512
	global_load_dwordx4 v[200:203], v[18:19], off offset:576
	v_add_u32_e32 v32, 0xffffe010, v3
	v_ashrrev_i32_e32 v32, 5, v32
	v_add_u32_e32 v32, 2, v32
	v_mad_i64_i32 v[186:187], s[40:41], v32, s59, v[8:9]
	v_lshl_add_u64 v[186:187], v[186:187], 0, v[10:11]
	global_load_dwordx4 v[204:207], v[186:187], off
	global_load_dwordx4 v[208:211], v[186:187], off offset:64
	global_load_dwordx4 v[212:215], v[186:187], off offset:512
	global_load_dwordx4 v[216:219], v[186:187], off offset:576
	v_add_u32_e32 v32, 0xffffe020, v3
	v_ashrrev_i32_e32 v32, 5, v32
	v_add_u32_e32 v32, 2, v32
	v_mad_i64_i32 v[186:187], s[40:41], v32, s59, v[8:9]
	v_lshl_add_u64 v[186:187], v[186:187], 0, v[10:11]
	global_load_dwordx4 v[220:223], v[186:187], off
	global_load_dwordx4 v[224:227], v[186:187], off offset:64
	global_load_dwordx4 v[228:231], v[186:187], off offset:512
	global_load_dwordx4 v[232:235], v[186:187], off offset:576
	v_add_u32_e32 v32, 0xffffe030, v3
	v_ashrrev_i32_e32 v32, 5, v32
	v_add_u32_e32 v32, 2, v32
	v_mad_i64_i32 v[186:187], s[40:41], v32, s59, v[8:9]
	v_lshl_add_u64 v[186:187], v[186:187], 0, v[10:11]
	global_load_dwordx4 v[236:239], v[186:187], off
	global_load_dwordx4 v[240:243], v[186:187], off offset:64
	global_load_dwordx4 v[244:247], v[186:187], off offset:512
	global_load_dwordx4 v[248:251], v[186:187], off offset:576
	v_add_u32_e32 v32, 0xffffe080, v3
	v_ashrrev_i32_e32 v32, 5, v32
	v_add_u32_e32 v32, 2, v32
	v_mad_i64_i32 v[24:25], s[40:41], v32, s59, v[8:9]
	v_lshl_add_u64 v[24:25], v[24:25], 0, v[10:11]
	v_add_u32_e32 v32, 0xffffe090, v3
	v_ashrrev_i32_e32 v32, 5, v32
	v_add_u32_e32 v32, 2, v32
	v_mad_i64_i32 v[26:27], s[40:41], v32, s59, v[8:9]
	v_lshl_add_u64 v[26:27], v[26:27], 0, v[10:11]
	v_add_u32_e32 v32, 0xffffe0a0, v3
	v_ashrrev_i32_e32 v32, 5, v32
	v_add_u32_e32 v32, 2, v32
	v_mad_i64_i32 v[28:29], s[40:41], v32, s59, v[8:9]
	v_lshl_add_u64 v[28:29], v[28:29], 0, v[10:11]
	s_ashr_i32 s39, s38, 31
	s_lshl_b64 s[40:41], s[8:9], 22
	s_lshl_b64 s[42:43], s[38:39], 21
	s_add_u32 s8, s53, s40
	s_addc_u32 s29, s54, s41
	v_ashrrev_i32_e32 v7, 31, v6
	s_add_u32 s40, s8, s42
	v_lshlrev_b64 v[20:21], 13, v[6:7]
	s_addc_u32 s41, s29, s43
	v_lshlrev_b64 v[12:13], 1, v[4:5]
	v_lshl_add_u64 v[20:21], s[40:41], 0, v[20:21]
	v_lshl_add_u64 v[20:21], v[20:21], 0, v[12:13]
	v_add_co_u32_e32 v22, vcc, s62, v20
	v_add_u32_e32 v7, 0xffffe010, v3
	s_nop 0
	v_addc_co_u32_e32 v23, vcc, -1, v21, vcc
	v_lshl_add_u64 v[20:21], v[20:21], 0, s[20:21]
	v_ashrrev_i32_e32 v7, 5, v7
	v_add_u32_e32 v7, 2, v7
	s_waitcnt vmcnt(15)
	v_pk_mul_f32 v[188:189], v[188:189], s[18:19] op_sel_hi:[1,0]
	v_pk_mul_f32 v[190:191], v[190:191], s[18:19] op_sel_hi:[1,0]
	v_pk_mul_f32 v[188:189], v[158:159], v[188:189]
	v_pk_mul_f32 v[190:191], v[160:161], v[190:191]
	v_cvt_pk_bf16_f32 v188, v188, v189
	s_nop 0
	v_cvt_pk_bf16_f32 v189, v190, v191
	global_store_dwordx2 v[22:23], v[188:189], off
	global_load_dwordx4 v[188:191], v[24:25], off
	s_waitcnt vmcnt(16)
	v_pk_mul_f32 v[192:193], v[192:193], s[18:19] op_sel_hi:[1,0]
	v_pk_mul_f32 v[194:195], v[194:195], s[18:19] op_sel_hi:[1,0]
	v_pk_mul_f32 v[192:193], v[154:155], v[192:193]
	v_pk_mul_f32 v[194:195], v[156:157], v[194:195]
	v_cvt_pk_bf16_f32 v192, v192, v193
	s_nop 0
	v_cvt_pk_bf16_f32 v193, v194, v195
	global_store_dwordx2 v[20:21], v[192:193], off offset:32
	global_load_dwordx4 v[192:195], v[24:25], off offset:64
	s_waitcnt vmcnt(17)
	v_pk_mul_f32 v[196:197], v[196:197], s[18:19] op_sel_hi:[1,0]
	v_pk_mul_f32 v[198:199], v[198:199], s[18:19] op_sel_hi:[1,0]
	v_pk_mul_f32 v[196:197], v[146:147], v[196:197]
	v_pk_mul_f32 v[198:199], v[148:149], v[198:199]
	v_cvt_pk_bf16_f32 v196, v196, v197
	s_nop 0
	v_cvt_pk_bf16_f32 v197, v198, v199
	global_store_dwordx2 v[20:21], v[196:197], off offset:256
	global_load_dwordx4 v[196:199], v[24:25], off offset:512
	v_mad_i64_i32 v[18:19], s[42:43], v7, s59, v[8:9]
	v_lshl_add_u64 v[18:19], v[18:19], 0, v[10:11]
	v_add_u32_e32 v7, 0xffffe020, v3
	v_ashrrev_i32_e32 v7, 5, v7
	v_add_u32_e32 v7, 2, v7
	s_waitcnt vmcnt(18)
	v_pk_mul_f32 v[200:201], v[200:201], s[18:19] op_sel_hi:[1,0]
	v_pk_mul_f32 v[202:203], v[202:203], s[18:19] op_sel_hi:[1,0]
	v_pk_mul_f32 v[200:201], v[142:143], v[200:201]
	v_pk_mul_f32 v[202:203], v[144:145], v[202:203]
	v_cvt_pk_bf16_f32 v200, v200, v201
	s_nop 0
	v_cvt_pk_bf16_f32 v201, v202, v203
	global_store_dwordx2 v[20:21], v[200:201], off offset:288
	global_load_dwordx4 v[200:203], v[24:25], off offset:576
	v_add_u32_e32 v20, 16, v6
	v_ashrrev_i32_e32 v21, 31, v20
	v_lshlrev_b64 v[20:21], 13, v[20:21]
	v_lshl_add_u64 v[20:21], s[40:41], 0, v[20:21]
	v_lshl_add_u64 v[20:21], v[20:21], 0, v[12:13]
	v_add_co_u32_e32 v22, vcc, s62, v20
	s_waitcnt vmcnt(19)
	v_pk_mul_f32 v[204:205], v[204:205], s[18:19] op_sel_hi:[1,0]
	v_addc_co_u32_e32 v23, vcc, -1, v21, vcc
	v_pk_mul_f32 v[206:207], v[206:207], s[18:19] op_sel_hi:[1,0]
	v_pk_mul_f32 v[204:205], v[150:151], v[204:205]
	v_pk_mul_f32 v[206:207], v[152:153], v[206:207]
	v_cvt_pk_bf16_f32 v204, v204, v205
	v_lshl_add_u64 v[20:21], v[20:21], 0, s[20:21]
	v_cvt_pk_bf16_f32 v205, v206, v207
	global_store_dwordx2 v[22:23], v[204:205], off
	global_load_dwordx4 v[204:207], v[26:27], off
	s_waitcnt vmcnt(20)
	v_pk_mul_f32 v[208:209], v[208:209], s[18:19] op_sel_hi:[1,0]
	v_pk_mul_f32 v[210:211], v[210:211], s[18:19] op_sel_hi:[1,0]
	v_pk_mul_f32 v[208:209], v[138:139], v[208:209]
	v_pk_mul_f32 v[210:211], v[140:141], v[210:211]
	v_cvt_pk_bf16_f32 v208, v208, v209
	s_nop 0
	v_cvt_pk_bf16_f32 v209, v210, v211
	global_store_dwordx2 v[20:21], v[208:209], off offset:32
	global_load_dwordx4 v[208:211], v[26:27], off offset:64
	s_waitcnt vmcnt(21)
	v_pk_mul_f32 v[212:213], v[212:213], s[18:19] op_sel_hi:[1,0]
	v_pk_mul_f32 v[214:215], v[214:215], s[18:19] op_sel_hi:[1,0]
	v_pk_mul_f32 v[212:213], v[134:135], v[212:213]
	v_pk_mul_f32 v[214:215], v[136:137], v[214:215]
	v_cvt_pk_bf16_f32 v212, v212, v213
	s_nop 0
	v_cvt_pk_bf16_f32 v213, v214, v215
	global_store_dwordx2 v[20:21], v[212:213], off offset:256
	global_load_dwordx4 v[212:215], v[26:27], off offset:512
	v_mad_i64_i32 v[18:19], s[42:43], v7, s59, v[8:9]
	v_lshl_add_u64 v[18:19], v[18:19], 0, v[10:11]
	v_add_u32_e32 v7, 0xffffe030, v3
	v_ashrrev_i32_e32 v7, 5, v7
	v_add_u32_e32 v7, 2, v7
	s_waitcnt vmcnt(22)
	v_pk_mul_f32 v[216:217], v[216:217], s[18:19] op_sel_hi:[1,0]
	v_pk_mul_f32 v[218:219], v[218:219], s[18:19] op_sel_hi:[1,0]
	v_pk_mul_f32 v[216:217], v[126:127], v[216:217]
	v_pk_mul_f32 v[218:219], v[128:129], v[218:219]
	v_cvt_pk_bf16_f32 v216, v216, v217
	s_nop 0
	v_cvt_pk_bf16_f32 v217, v218, v219
	global_store_dwordx2 v[20:21], v[216:217], off offset:288
	global_load_dwordx4 v[216:219], v[26:27], off offset:576
	v_add_u32_e32 v20, 32, v6
	v_ashrrev_i32_e32 v21, 31, v20
	v_lshlrev_b64 v[20:21], 13, v[20:21]
	v_lshl_add_u64 v[20:21], s[40:41], 0, v[20:21]
	v_lshl_add_u64 v[20:21], v[20:21], 0, v[12:13]
	v_add_co_u32_e32 v22, vcc, s62, v20
	s_waitcnt vmcnt(23)
	v_pk_mul_f32 v[220:221], v[220:221], s[18:19] op_sel_hi:[1,0]
	v_addc_co_u32_e32 v23, vcc, -1, v21, vcc
	v_pk_mul_f32 v[222:223], v[222:223], s[18:19] op_sel_hi:[1,0]
	v_pk_mul_f32 v[220:221], v[130:131], v[220:221]
	v_pk_mul_f32 v[222:223], v[132:133], v[222:223]
	v_cvt_pk_bf16_f32 v220, v220, v221
	v_lshl_add_u64 v[20:21], v[20:21], 0, s[20:21]
	v_cvt_pk_bf16_f32 v221, v222, v223
	global_store_dwordx2 v[22:23], v[220:221], off
	global_load_dwordx4 v[220:223], v[28:29], off
	s_waitcnt vmcnt(24)
	v_pk_mul_f32 v[224:225], v[224:225], s[18:19] op_sel_hi:[1,0]
	v_pk_mul_f32 v[226:227], v[226:227], s[18:19] op_sel_hi:[1,0]
	v_pk_mul_f32 v[224:225], v[122:123], v[224:225]
	v_pk_mul_f32 v[226:227], v[124:125], v[226:227]
	v_cvt_pk_bf16_f32 v224, v224, v225
	s_nop 0
	v_cvt_pk_bf16_f32 v225, v226, v227
	global_store_dwordx2 v[20:21], v[224:225], off offset:32
	global_load_dwordx4 v[224:227], v[28:29], off offset:64
	s_waitcnt vmcnt(25)
	v_pk_mul_f32 v[228:229], v[228:229], s[18:19] op_sel_hi:[1,0]
	v_pk_mul_f32 v[230:231], v[230:231], s[18:19] op_sel_hi:[1,0]
	v_pk_mul_f32 v[228:229], v[118:119], v[228:229]
	v_pk_mul_f32 v[230:231], v[120:121], v[230:231]
	v_cvt_pk_bf16_f32 v228, v228, v229
	s_nop 0
	v_cvt_pk_bf16_f32 v229, v230, v231
	global_store_dwordx2 v[20:21], v[228:229], off offset:256
	global_load_dwordx4 v[228:231], v[28:29], off offset:512
	v_mad_i64_i32 v[18:19], s[42:43], v7, s59, v[8:9]
	v_lshl_add_u64 v[18:19], v[18:19], 0, v[10:11]
	v_add_u32_e32 v7, 0xffffe080, v3
	v_ashrrev_i32_e32 v7, 5, v7
	v_add_u32_e32 v7, 2, v7
	s_waitcnt vmcnt(26)
	v_pk_mul_f32 v[232:233], v[232:233], s[18:19] op_sel_hi:[1,0]
	v_pk_mul_f32 v[234:235], v[234:235], s[18:19] op_sel_hi:[1,0]
	v_pk_mul_f32 v[232:233], v[110:111], v[232:233]
	v_pk_mul_f32 v[234:235], v[112:113], v[234:235]
	v_cvt_pk_bf16_f32 v232, v232, v233
	s_nop 0
	v_cvt_pk_bf16_f32 v233, v234, v235
	global_store_dwordx2 v[20:21], v[232:233], off offset:288
	global_load_dwordx4 v[232:235], v[28:29], off offset:576
	v_add_u32_e32 v20, 48, v6
	v_ashrrev_i32_e32 v21, 31, v20
	v_lshlrev_b64 v[20:21], 13, v[20:21]
	v_lshl_add_u64 v[20:21], s[40:41], 0, v[20:21]
	v_lshl_add_u64 v[20:21], v[20:21], 0, v[12:13]
	v_add_co_u32_e32 v22, vcc, s62, v20
	s_waitcnt vmcnt(27)
	v_pk_mul_f32 v[236:237], v[236:237], s[18:19] op_sel_hi:[1,0]
	v_addc_co_u32_e32 v23, vcc, -1, v21, vcc
	v_pk_mul_f32 v[238:239], v[238:239], s[18:19] op_sel_hi:[1,0]
	v_pk_mul_f32 v[236:237], v[114:115], v[236:237]
	v_pk_mul_f32 v[238:239], v[116:117], v[238:239]
	v_cvt_pk_bf16_f32 v236, v236, v237
	v_lshl_add_u64 v[20:21], v[20:21], 0, s[20:21]
	v_cvt_pk_bf16_f32 v237, v238, v239
	global_store_dwordx2 v[22:23], v[236:237], off
	s_waitcnt vmcnt(27)
	v_pk_mul_f32 v[240:241], v[240:241], s[18:19] op_sel_hi:[1,0]
	v_pk_mul_f32 v[242:243], v[242:243], s[18:19] op_sel_hi:[1,0]
	v_pk_mul_f32 v[240:241], v[106:107], v[240:241]
	v_pk_mul_f32 v[242:243], v[108:109], v[242:243]
	v_cvt_pk_bf16_f32 v240, v240, v241
	s_nop 0
	v_cvt_pk_bf16_f32 v241, v242, v243
	global_store_dwordx2 v[20:21], v[240:241], off offset:32
	s_waitcnt vmcnt(27)
	v_pk_mul_f32 v[244:245], v[244:245], s[18:19] op_sel_hi:[1,0]
	v_pk_mul_f32 v[246:247], v[246:247], s[18:19] op_sel_hi:[1,0]
	v_pk_mul_f32 v[244:245], v[102:103], v[244:245]
	v_pk_mul_f32 v[246:247], v[104:105], v[246:247]
	v_cvt_pk_bf16_f32 v244, v244, v245
	s_nop 0
	v_cvt_pk_bf16_f32 v245, v246, v247
	global_store_dwordx2 v[20:21], v[244:245], off offset:256
	v_mad_i64_i32 v[18:19], s[42:43], v7, s59, v[8:9]
	v_lshl_add_u64 v[18:19], v[18:19], 0, v[10:11]
	v_add_u32_e32 v7, 0xffffe090, v3
	v_ashrrev_i32_e32 v7, 5, v7
	v_add_u32_e32 v7, 2, v7
	s_waitcnt vmcnt(27)
	v_pk_mul_f32 v[248:249], v[248:249], s[18:19] op_sel_hi:[1,0]
	v_pk_mul_f32 v[250:251], v[250:251], s[18:19] op_sel_hi:[1,0]
	v_pk_mul_f32 v[248:249], v[98:99], v[248:249]
	v_pk_mul_f32 v[250:251], v[100:101], v[250:251]
	v_cvt_pk_bf16_f32 v248, v248, v249
	s_nop 0
	v_cvt_pk_bf16_f32 v249, v250, v251
	global_store_dwordx2 v[20:21], v[248:249], off offset:288
	v_add_u32_e32 v20, 0x80, v6
	v_ashrrev_i32_e32 v21, 31, v20
	v_lshlrev_b64 v[20:21], 13, v[20:21]
	v_lshl_add_u64 v[20:21], s[40:41], 0, v[20:21]
	v_lshl_add_u64 v[20:21], v[20:21], 0, v[12:13]
	v_add_co_u32_e32 v22, vcc, s62, v20
	s_waitcnt vmcnt(26)
	v_pk_mul_f32 v[188:189], v[188:189], s[18:19] op_sel_hi:[1,0]
	v_addc_co_u32_e32 v23, vcc, -1, v21, vcc
	v_pk_mul_f32 v[190:191], v[190:191], s[18:19] op_sel_hi:[1,0]
	v_pk_mul_f32 v[188:189], v[94:95], v[188:189]
	v_pk_mul_f32 v[190:191], v[96:97], v[190:191]
	v_cvt_pk_bf16_f32 v188, v188, v189
	v_lshl_add_u64 v[20:21], v[20:21], 0, s[20:21]
	v_cvt_pk_bf16_f32 v189, v190, v191
	global_store_dwordx2 v[22:23], v[188:189], off
	s_waitcnt vmcnt(25)
	v_pk_mul_f32 v[192:193], v[192:193], s[18:19] op_sel_hi:[1,0]
	v_pk_mul_f32 v[194:195], v[194:195], s[18:19] op_sel_hi:[1,0]
	v_pk_mul_f32 v[192:193], v[90:91], v[192:193]
	v_pk_mul_f32 v[194:195], v[92:93], v[194:195]
	v_cvt_pk_bf16_f32 v192, v192, v193
	s_nop 0
	v_cvt_pk_bf16_f32 v193, v194, v195
	global_store_dwordx2 v[20:21], v[192:193], off offset:32
	s_waitcnt vmcnt(24)
	v_pk_mul_f32 v[196:197], v[196:197], s[18:19] op_sel_hi:[1,0]
	v_pk_mul_f32 v[198:199], v[198:199], s[18:19] op_sel_hi:[1,0]
	v_pk_mul_f32 v[196:197], v[86:87], v[196:197]
	v_pk_mul_f32 v[198:199], v[88:89], v[198:199]
	v_cvt_pk_bf16_f32 v196, v196, v197
	s_nop 0
	v_cvt_pk_bf16_f32 v197, v198, v199
	global_store_dwordx2 v[20:21], v[196:197], off offset:256
	v_mad_i64_i32 v[18:19], s[42:43], v7, s59, v[8:9]
	v_lshl_add_u64 v[18:19], v[18:19], 0, v[10:11]
	v_add_u32_e32 v7, 0xffffe0a0, v3
	v_ashrrev_i32_e32 v7, 5, v7
	v_add_u32_e32 v7, 2, v7
	v_add_u32_e32 v3, 0xffffe0b0, v3
	v_ashrrev_i32_e32 v3, 5, v3
	v_add_u32_e32 v3, 2, v3
	s_waitcnt vmcnt(23)
	v_pk_mul_f32 v[200:201], v[200:201], s[18:19] op_sel_hi:[1,0]
	v_pk_mul_f32 v[202:203], v[202:203], s[18:19] op_sel_hi:[1,0]
	v_pk_mul_f32 v[200:201], v[78:79], v[200:201]
	v_pk_mul_f32 v[202:203], v[80:81], v[202:203]
	v_cvt_pk_bf16_f32 v200, v200, v201
	s_nop 0
	v_cvt_pk_bf16_f32 v201, v202, v203
	global_store_dwordx2 v[20:21], v[200:201], off offset:288
	v_add_u32_e32 v20, 0x90, v6
	v_ashrrev_i32_e32 v21, 31, v20
	v_lshlrev_b64 v[20:21], 13, v[20:21]
	v_lshl_add_u64 v[20:21], s[40:41], 0, v[20:21]
	v_lshl_add_u64 v[20:21], v[20:21], 0, v[12:13]
	v_add_co_u32_e32 v22, vcc, s62, v20
	s_waitcnt vmcnt(22)
	v_pk_mul_f32 v[204:205], v[204:205], s[18:19] op_sel_hi:[1,0]
	v_addc_co_u32_e32 v23, vcc, -1, v21, vcc
	v_pk_mul_f32 v[206:207], v[206:207], s[18:19] op_sel_hi:[1,0]
	v_pk_mul_f32 v[204:205], v[82:83], v[204:205]
	v_pk_mul_f32 v[206:207], v[84:85], v[206:207]
	v_cvt_pk_bf16_f32 v204, v204, v205
	v_lshl_add_u64 v[20:21], v[20:21], 0, s[20:21]
	v_cvt_pk_bf16_f32 v205, v206, v207
	global_store_dwordx2 v[22:23], v[204:205], off
	s_waitcnt vmcnt(21)
	v_pk_mul_f32 v[208:209], v[208:209], s[18:19] op_sel_hi:[1,0]
	v_pk_mul_f32 v[210:211], v[210:211], s[18:19] op_sel_hi:[1,0]
	v_pk_mul_f32 v[208:209], v[74:75], v[208:209]
	v_pk_mul_f32 v[210:211], v[76:77], v[210:211]
	v_cvt_pk_bf16_f32 v208, v208, v209
	s_nop 0
	v_cvt_pk_bf16_f32 v209, v210, v211
	global_store_dwordx2 v[20:21], v[208:209], off offset:32
	s_waitcnt vmcnt(20)
	v_pk_mul_f32 v[212:213], v[212:213], s[18:19] op_sel_hi:[1,0]
	v_pk_mul_f32 v[214:215], v[214:215], s[18:19] op_sel_hi:[1,0]
	v_pk_mul_f32 v[212:213], v[70:71], v[212:213]
	v_pk_mul_f32 v[214:215], v[72:73], v[214:215]
	v_cvt_pk_bf16_f32 v212, v212, v213
	s_nop 0
	v_cvt_pk_bf16_f32 v213, v214, v215
	global_store_dwordx2 v[20:21], v[212:213], off offset:256
	v_mad_i64_i32 v[18:19], s[42:43], v7, s59, v[8:9]
	v_lshl_add_u64 v[18:19], v[18:19], 0, v[10:11]
	v_mad_i64_i32 v[8:9], s[42:43], v3, s59, v[8:9]
	s_waitcnt vmcnt(19)
	v_pk_mul_f32 v[216:217], v[216:217], s[18:19] op_sel_hi:[1,0]
	v_pk_mul_f32 v[218:219], v[218:219], s[18:19] op_sel_hi:[1,0]
	v_pk_mul_f32 v[216:217], v[62:63], v[216:217]
	v_pk_mul_f32 v[218:219], v[64:65], v[218:219]
	v_cvt_pk_bf16_f32 v216, v216, v217
	s_nop 0
	v_cvt_pk_bf16_f32 v217, v218, v219
	global_store_dwordx2 v[20:21], v[216:217], off offset:288
	v_add_u32_e32 v20, 0xa0, v6
	v_ashrrev_i32_e32 v21, 31, v20
	v_lshlrev_b64 v[20:21], 13, v[20:21]
	v_lshl_add_u64 v[20:21], s[40:41], 0, v[20:21]
	v_lshl_add_u64 v[20:21], v[20:21], 0, v[12:13]
	v_add_co_u32_e32 v22, vcc, s62, v20
	v_add_u32_e32 v6, 0xb0, v6
	s_nop 0
	v_addc_co_u32_e32 v23, vcc, -1, v21, vcc
	v_lshl_add_u64 v[20:21], v[20:21], 0, s[20:21]
	v_ashrrev_i32_e32 v7, 31, v6
	v_lshlrev_b64 v[6:7], 13, v[6:7]
	v_lshl_add_u64 v[6:7], s[40:41], 0, v[6:7]
	v_lshl_add_u64 v[12:13], v[6:7], 0, v[12:13]
	v_add_co_u32_e32 v6, vcc, s62, v12
	s_nop 1
	v_addc_co_u32_e32 v7, vcc, -1, v13, vcc
	s_waitcnt vmcnt(18)
	v_pk_mul_f32 v[220:221], v[220:221], s[18:19] op_sel_hi:[1,0]
	v_pk_mul_f32 v[222:223], v[222:223], s[18:19] op_sel_hi:[1,0]
	v_pk_mul_f32 v[220:221], v[66:67], v[220:221]
	v_pk_mul_f32 v[222:223], v[68:69], v[222:223]
	v_cvt_pk_bf16_f32 v220, v220, v221
	s_nop 0
	v_cvt_pk_bf16_f32 v221, v222, v223
	global_store_dwordx2 v[22:23], v[220:221], off
	s_waitcnt vmcnt(17)
	v_pk_mul_f32 v[224:225], v[224:225], s[18:19] op_sel_hi:[1,0]
	v_pk_mul_f32 v[226:227], v[226:227], s[18:19] op_sel_hi:[1,0]
	v_pk_mul_f32 v[224:225], v[58:59], v[224:225]
	v_pk_mul_f32 v[226:227], v[60:61], v[226:227]
	v_cvt_pk_bf16_f32 v224, v224, v225
	s_nop 0
	v_cvt_pk_bf16_f32 v225, v226, v227
	global_store_dwordx2 v[20:21], v[224:225], off offset:32
	s_waitcnt vmcnt(16)
	v_pk_mul_f32 v[228:229], v[228:229], s[18:19] op_sel_hi:[1,0]
	v_pk_mul_f32 v[230:231], v[230:231], s[18:19] op_sel_hi:[1,0]
	v_pk_mul_f32 v[228:229], v[54:55], v[228:229]
	v_pk_mul_f32 v[230:231], v[56:57], v[230:231]
	v_cvt_pk_bf16_f32 v228, v228, v229
	s_nop 0
	v_cvt_pk_bf16_f32 v229, v230, v231
	global_store_dwordx2 v[20:21], v[228:229], off offset:256
	v_lshl_add_u64 v[18:19], v[8:9], 0, v[10:11]
	s_waitcnt vmcnt(15)
	v_pk_mul_f32 v[10:11], v[232:233], s[18:19] op_sel_hi:[1,0]
	v_pk_mul_f32 v[8:9], v[234:235], s[18:19] op_sel_hi:[1,0]
	v_pk_mul_f32 v[10:11], v[46:47], v[10:11]
	v_pk_mul_f32 v[8:9], v[48:49], v[8:9]
	v_cvt_pk_bf16_f32 v10, v10, v11
	s_nop 0
	v_cvt_pk_bf16_f32 v11, v8, v9
	global_store_dwordx2 v[20:21], v[10:11], off offset:288
	global_load_dwordx4 v[8:11], v[18:19], off
	s_waitcnt vmcnt(0)
	v_pk_mul_f32 v[8:9], v[8:9], s[18:19] op_sel_hi:[1,0]
	v_pk_mul_f32 v[10:11], v[10:11], s[18:19] op_sel_hi:[1,0]
	v_pk_mul_f32 v[8:9], v[50:51], v[8:9]
	v_pk_mul_f32 v[10:11], v[52:53], v[10:11]
	v_cvt_pk_bf16_f32 v8, v8, v9
	s_nop 0
	v_cvt_pk_bf16_f32 v9, v10, v11
	global_store_dwordx2 v[6:7], v[8:9], off
	global_load_dwordx4 v[6:9], v[18:19], off offset:64
	v_lshl_add_u64 v[10:11], v[12:13], 0, s[20:21]
	s_waitcnt vmcnt(0)
	v_pk_mul_f32 v[6:7], v[6:7], s[18:19] op_sel_hi:[1,0]
	v_pk_mul_f32 v[8:9], v[8:9], s[18:19] op_sel_hi:[1,0]
	v_pk_mul_f32 v[6:7], v[42:43], v[6:7]
	v_pk_mul_f32 v[8:9], v[44:45], v[8:9]
	v_cvt_pk_bf16_f32 v6, v6, v7
	s_nop 0
	v_cvt_pk_bf16_f32 v7, v8, v9
	global_store_dwordx2 v[10:11], v[6:7], off offset:32
	global_load_dwordx4 v[6:9], v[18:19], off offset:512
	s_waitcnt vmcnt(0)
	v_pk_mul_f32 v[6:7], v[6:7], s[18:19] op_sel_hi:[1,0]
	v_pk_mul_f32 v[8:9], v[8:9], s[18:19] op_sel_hi:[1,0]
	v_pk_mul_f32 v[6:7], v[38:39], v[6:7]
	v_pk_mul_f32 v[8:9], v[40:41], v[8:9]
	v_cvt_pk_bf16_f32 v6, v6, v7
	s_nop 0
	v_cvt_pk_bf16_f32 v7, v8, v9
	global_store_dwordx2 v[10:11], v[6:7], off offset:256
	global_load_dwordx4 v[6:9], v[18:19], off offset:576
	s_waitcnt vmcnt(0)
	v_pk_mul_f32 v[6:7], v[6:7], s[18:19] op_sel_hi:[1,0]
	v_pk_mul_f32 v[8:9], v[8:9], s[18:19] op_sel_hi:[1,0]
	v_pk_mul_f32 v[6:7], v[34:35], v[6:7]
	v_pk_mul_f32 v[8:9], v[36:37], v[8:9]
	v_cvt_pk_bf16_f32 v6, v6, v7
	s_nop 0
	v_cvt_pk_bf16_f32 v7, v8, v9
	global_store_dwordx2 v[10:11], v[6:7], off offset:288
	s_cbranch_execz .LBB0_1697
